# v30 with nt policy extended to the last-use streaming loads of all stream-update loops
# baseline (speedup 1.0000x reference)
.LBB0_625:
	v_readlane_b32 s6, v255, 31
	v_readlane_b32 s7, v255, 32
	s_mov_b64 s[4:5], -1
	s_and_b64 vcc, exec, s[6:7]
	s_cbranch_vccz .LBB0_712
	v_mov_b32_e32 v0, v157
	v_readlane_b32 s4, v255, 0
	v_ashrrev_i32_e32 v1, 6, v0
	s_nop 0
	v_add_u32_e32 v54, s4, v1
	v_cmp_gt_i32_e32 vcc, s81, v54
	s_and_saveexec_b64 s[4:5], vcc
	s_cbranch_execz .LBB0_645
	v_and_b32_e32 v34, 63, v0
	v_readlane_b32 s6, v255, 25
	v_ashrrev_i32_e32 v55, 31, v54
	v_lshlrev_b32_e32 v12, 5, v34
	v_readlane_b32 s7, v255, 26
	v_lshlrev_b64 v[24:25], 11, v[54:55]
	s_nop 3
	global_load_dwordx4 v[0:3], v12, s[6:7] offset:16
	global_load_dwordx4 v[4:7], v12, s[6:7]
	global_load_dwordx4 v[8:11], v12, s[6:7] offset:2064
	s_nop 0
	global_load_dwordx4 v[12:15], v12, s[6:7] offset:2048
	v_lshl_or_b32 v24, v34, 4, v24
	v_lshl_add_u64 v[20:21], s[52:53], 0, v[24:25]
	v_lshl_add_u64 v[28:29], s[60:61], 0, v[24:25]
	global_load_dwordx4 v[16:19], v[20:21], off nt
	s_nop 0
	global_load_dwordx4 v[20:23], v[20:21], off offset:1024 nt
	s_nop 0
	global_load_dwordx4 v[24:27], v[28:29], off nt
	s_nop 0
	global_load_dwordx4 v[28:31], v[28:29], off offset:1024 nt
	v_cmp_gt_u32_e32 vcc, 16, v34
	v_mov_b32_e32 v57, 0
	v_lshlrev_b32_e32 v32, 2, v34
	s_and_saveexec_b64 s[6:7], vcc
	s_cbranch_execz .LBB0_629
	v_lshlrev_b64 v[36:37], 6, v[54:55]
	v_lshl_add_u64 v[36:37], s[44:45], 0, v[36:37]
	v_mov_b32_e32 v33, v113
	v_lshl_add_u64 v[36:37], v[36:37], 0, v[32:33]
	global_load_dword v57, v[36:37], off

.LBB0_632:
	v_add_u32_e32 v52, s14, v54
	v_cmp_gt_i32_e64 s[10:11], s81, v52
	v_ashrrev_i32_e32 v53, 31, v52
	s_and_saveexec_b64 s[6:7], s[10:11]
	s_cbranch_execz .LBB0_636
	v_lshlrev_b64 v[40:41], 11, v[52:53]
	v_lshl_or_b32 v40, v56, 1, v40
	v_lshl_add_u64 v[36:37], s[52:53], 0, v[40:41]
	v_lshl_add_u64 v[40:41], s[60:61], 0, v[40:41]
	global_load_dwordx4 v[32:35], v[36:37], off nt
	s_nop 0
	global_load_dwordx4 v[36:39], v[36:37], off offset:1024 nt
	s_nop 0
	global_load_dwordx4 v[44:47], v[40:41], off nt
	s_nop 0
	global_load_dwordx4 v[40:43], v[40:41], off offset:1024 nt
	v_mov_b32_e32 v64, 0
	s_and_saveexec_b64 s[12:13], vcc
	s_cbranch_execz .LBB0_635
	v_lshlrev_b64 v[64:65], 6, v[52:53]
	v_lshl_add_u64 v[64:65], v[50:51], 0, v[64:65]
	global_load_dword v64, v[64:65], off
	s_or_b64 exec, exec, s[12:13]
	s_or_b64 exec, exec, s[6:7]
	s_waitcnt vmcnt(5) lgkmcnt(0)
	s_branch .Le0_p1

.LBB0_638:
	s_or_b64 exec, exec, s[6:7]
	s_and_saveexec_b64 s[12:13], s[10:11]
	s_cbranch_execz .LBB0_631
	v_add_u32_e32 v54, s18, v54
	v_cmp_gt_i32_e64 s[10:11], s81, v54
	s_and_saveexec_b64 s[6:7], s[10:11]
	s_cbranch_execz .LBB0_643
	v_ashrrev_i32_e32 v55, 31, v54
	v_lshlrev_b64 v[24:25], 11, v[54:55]
	v_lshl_or_b32 v24, v56, 1, v24
	v_lshl_add_u64 v[20:21], s[52:53], 0, v[24:25]
	v_lshl_add_u64 v[28:29], s[60:61], 0, v[24:25]
	global_load_dwordx4 v[16:19], v[20:21], off nt
	s_nop 0
	global_load_dwordx4 v[20:23], v[20:21], off offset:1024 nt
	s_nop 0
	global_load_dwordx4 v[24:27], v[28:29], off nt
	s_nop 0
	global_load_dwordx4 v[28:31], v[28:29], off offset:1024 nt
	v_mov_b32_e32 v57, 0
	s_and_saveexec_b64 s[10:11], vcc
	s_cbranch_execz .LBB0_642
	v_lshlrev_b64 v[54:55], 6, v[54:55]
	v_lshl_add_u64 v[54:55], v[50:51], 0, v[54:55]
	global_load_dword v57, v[54:55], off
	s_or_b64 exec, exec, s[10:11]
	s_or_b64 exec, exec, s[6:7]
	s_waitcnt vmcnt(5)
	s_branch .Le0_p2

.LBB0_712:
	s_and_b64 vcc, exec, s[4:5]
	s_cbranch_vccz .LBB0_199
	v_mov_b32_e32 v0, v157
	v_readlane_b32 s4, v255, 0
	v_ashrrev_i32_e32 v1, 6, v0
	s_nop 0
	v_add_u32_e32 v70, s4, v1
	v_cmp_gt_i32_e32 vcc, s81, v70
	s_and_saveexec_b64 s[4:5], vcc
	s_cbranch_execz .LBB0_732
	s_load_dwordx2 s[6:7], s[0:1], 0x40
	v_and_b32_e32 v42, 63, v0
	v_lshlrev_b32_e32 v12, 5, v42
	v_ashrrev_i32_e32 v71, 31, v70
	v_lshlrev_b32_e32 v72, 3, v42
	s_waitcnt lgkmcnt(0)
	global_load_dwordx4 v[0:3], v12, s[6:7] offset:16
	global_load_dwordx4 v[4:7], v12, s[6:7]
	global_load_dwordx4 v[8:11], v12, s[6:7] offset:2064
	s_nop 0
	global_load_dwordx4 v[12:15], v12, s[6:7] offset:2048
	s_load_dwordx2 s[6:7], s[0:1], 0x0
	v_lshlrev_b64 v[32:33], 10, v[70:71]
	v_or_b32_e32 v32, v32, v72
	v_lshl_add_u64 v[36:37], v[32:33], 1, s[60:61]
	v_cmp_gt_u32_e32 vcc, 16, v42
	s_waitcnt vmcnt(6) lgkmcnt(0)
	v_lshl_add_u64 v[28:29], v[32:33], 2, s[6:7]
	global_load_dwordx4 v[16:19], v[28:29], off offset:16 nt
	global_load_dwordx4 v[20:23], v[28:29], off nt
	global_load_dwordx4 v[24:27], v[28:29], off offset:2064 nt
	s_nop 0
	global_load_dwordx4 v[28:31], v[28:29], off offset:2048 nt
	s_nop 0
	global_load_dwordx4 v[32:35], v[36:37], off nt
	s_nop 0
	global_load_dwordx4 v[36:39], v[36:37], off offset:1024 nt
	v_mov_b32_e32 v73, 0
	v_lshlrev_b32_e32 v40, 2, v42
	s_and_saveexec_b64 s[6:7], vcc
	s_cbranch_execz .LBB0_716
	v_lshlrev_b64 v[44:45], 6, v[70:71]
	v_lshl_add_u64 v[44:45], s[44:45], 0, v[44:45]
	v_mov_b32_e32 v41, v113
	v_lshl_add_u64 v[44:45], v[44:45], 0, v[40:41]
	global_load_dword v73, v[44:45], off

.LBB0_719:
	v_add_u32_e32 v68, s14, v70
	v_cmp_gt_i32_e64 s[10:11], s81, v68
	v_ashrrev_i32_e32 v69, 31, v68
	s_and_saveexec_b64 s[6:7], s[10:11]
	s_cbranch_execz .LBB0_723
	s_load_dwordx2 s[12:13], s[0:1], 0x0
	v_lshlrev_b64 v[56:57], 10, v[68:69]
	v_or_b32_e32 v56, v56, v72
	v_mov_b32_e32 v80, 0
	s_waitcnt lgkmcnt(0)
	v_lshl_add_u64 v[48:49], v[56:57], 2, s[12:13]
	global_load_dwordx4 v[44:47], v[48:49], off offset:16 nt
	global_load_dwordx4 v[52:55], v[48:49], off nt
	global_load_dwordx4 v[40:43], v[48:49], off offset:2064 nt
	s_nop 0
	global_load_dwordx4 v[48:51], v[48:49], off offset:2048 nt
	v_lshl_add_u64 v[56:57], v[56:57], 1, s[60:61]
	global_load_dwordx4 v[60:63], v[56:57], off nt
	s_nop 0
	global_load_dwordx4 v[56:59], v[56:57], off offset:1024 nt
	s_and_saveexec_b64 s[12:13], vcc
	s_cbranch_execz .LBB0_722
	v_lshlrev_b64 v[80:81], 6, v[68:69]
	v_lshl_add_u64 v[80:81], v[66:67], 0, v[80:81]
	global_load_dword v80, v[80:81], off
	s_or_b64 exec, exec, s[12:13]
	s_or_b64 exec, exec, s[6:7]
	s_waitcnt vmcnt(7) lgkmcnt(0)
	s_branch .Le0_p3

.LBB0_725:
	s_or_b64 exec, exec, s[6:7]
	s_and_saveexec_b64 s[12:13], s[10:11]
	s_cbranch_execz .LBB0_718
	v_add_u32_e32 v70, s18, v70
	v_cmp_gt_i32_e64 s[10:11], s81, v70
	s_and_saveexec_b64 s[6:7], s[10:11]
	s_cbranch_execz .LBB0_730
	s_load_dwordx2 s[10:11], s[0:1], 0x0
	v_ashrrev_i32_e32 v71, 31, v70
	v_lshlrev_b64 v[32:33], 10, v[70:71]
	v_or_b32_e32 v32, v32, v72
	v_lshl_add_u64 v[36:37], v[32:33], 1, s[60:61]
	s_waitcnt lgkmcnt(0)
	v_lshl_add_u64 v[28:29], v[32:33], 2, s[10:11]
	global_load_dwordx4 v[16:19], v[28:29], off offset:16 nt
	global_load_dwordx4 v[20:23], v[28:29], off nt
	global_load_dwordx4 v[24:27], v[28:29], off offset:2064 nt
	s_nop 0
	global_load_dwordx4 v[28:31], v[28:29], off offset:2048 nt
	s_nop 0
	global_load_dwordx4 v[32:35], v[36:37], off nt
	s_nop 0
	global_load_dwordx4 v[36:39], v[36:37], off offset:1024 nt
	v_mov_b32_e32 v73, 0
	s_and_saveexec_b64 s[10:11], vcc
	s_cbranch_execz .LBB0_729
	v_lshlrev_b64 v[70:71], 6, v[70:71]
	v_lshl_add_u64 v[70:71], v[66:67], 0, v[70:71]
	global_load_dword v73, v[70:71], off
	s_or_b64 exec, exec, s[10:11]
	s_or_b64 exec, exec, s[6:7]
	s_waitcnt vmcnt(7)
	s_branch .Le0_p4

.LBB0_1182:
	v_add_u32_e32 v52, s28, v54
	v_cmp_gt_i32_e64 s[10:11], s33, v52
	v_ashrrev_i32_e32 v53, 31, v52
	s_and_saveexec_b64 s[6:7], s[10:11]
	s_cbranch_execz .LBB0_1186
	v_lshlrev_b64 v[40:41], 11, v[52:53]
	v_lshl_or_b32 v40, v56, 1, v40
	v_lshl_add_u64 v[36:37], s[56:57], 0, v[40:41]
	v_lshl_add_u64 v[40:41], s[20:21], 0, v[40:41]
	global_load_dwordx4 v[32:35], v[36:37], off nt
	s_nop 0
	global_load_dwordx4 v[36:39], v[36:37], off offset:1024 nt
	s_nop 0
	global_load_dwordx4 v[44:47], v[40:41], off nt
	s_nop 0
	global_load_dwordx4 v[40:43], v[40:41], off offset:1024 nt
	v_mov_b32_e32 v64, 0
	s_and_saveexec_b64 s[12:13], vcc
	s_cbranch_execz .LBB0_1185
	v_lshlrev_b64 v[64:65], 6, v[52:53]
	v_lshl_add_u64 v[64:65], v[50:51], 0, v[64:65]
	global_load_dword v64, v[64:65], off
	s_or_b64 exec, exec, s[12:13]
	s_or_b64 exec, exec, s[6:7]
	s_waitcnt vmcnt(5) lgkmcnt(0)
	s_branch .Le0_p5

.LBB0_1188:
	s_or_b64 exec, exec, s[6:7]
	s_and_saveexec_b64 s[12:13], s[10:11]
	s_cbranch_execz .LBB0_1181
	v_add_u32_e32 v54, s29, v54
	v_cmp_gt_i32_e64 s[10:11], s33, v54
	s_and_saveexec_b64 s[6:7], s[10:11]
	s_cbranch_execz .LBB0_1193
	v_ashrrev_i32_e32 v55, 31, v54
	v_lshlrev_b64 v[24:25], 11, v[54:55]
	v_lshl_or_b32 v24, v56, 1, v24
	v_lshl_add_u64 v[20:21], s[56:57], 0, v[24:25]
	v_lshl_add_u64 v[28:29], s[20:21], 0, v[24:25]
	global_load_dwordx4 v[16:19], v[20:21], off nt
	s_nop 0
	global_load_dwordx4 v[20:23], v[20:21], off offset:1024 nt
	s_nop 0
	global_load_dwordx4 v[24:27], v[28:29], off nt
	s_nop 0
	global_load_dwordx4 v[28:31], v[28:29], off offset:1024 nt
	v_mov_b32_e32 v57, 0
	s_and_saveexec_b64 s[10:11], vcc
	s_cbranch_execz .LBB0_1192
	v_lshlrev_b64 v[54:55], 6, v[54:55]
	v_lshl_add_u64 v[54:55], v[50:51], 0, v[54:55]
	global_load_dword v57, v[54:55], off
	s_or_b64 exec, exec, s[10:11]
	s_or_b64 exec, exec, s[6:7]
	s_waitcnt vmcnt(5)
	s_branch .Le0_p6
